# w_up fused conv epilogue: the 8 conv weight/bias vectors loaded once per tile before LDS staging (reused by both passes) instead of twice after the barriers
# speedup vs baseline: 1.0031x; 1.0003x over previous
; DI void gemm_tile(const GD& g, int pm, int pn, bf16_t* shm) {
;     ...
;               stgw[(m * 16 + fq * 4 + j) * 68 + bj * 32 + n * 16 + fr] = (g.epi == 3) ? acc[ai][bj][m][n][j] * rsc[ai * HALF + wr * 64 + m * 16 + fq * 4 + j] : acc[ai][bj][m][n][j];
;       __syncthreads();
;       if (g.epi == 3) {
;         const int cgp = lane & 7, rs = lane >> 3, r0 = rs * 8;
;         const int fcol = pn * HALF + wc * 32 + cgp * 4;
;         const float* cw = g.gnext;
;         const float4 wg0 = *reinterpret_cast<const float4*>(cw + fcol), wg1 = *reinterpret_cast<const float4*>(cw + NUP + fcol), wg2 = *reinterpret_cast<const float4*>(cw + 2 * NUP + fcol);
;         const float4 wv0 = *reinterpret_cast<const float4*>(cw + DFF + fcol), wv1 = *reinterpret_cast<const float4*>(cw + NUP + DFF + fcol), wv2 = *reinterpret_cast<const float4*>(cw + 2 * NUP + DFF + fcol);
;         const float4 bg = *reinterpret_cast<const float4*>(g.cbias + fcol), bv = *reinterpret_cast<const float4*>(g.cbias + DFF + fcol);
.LBB0_464:
	s_or_b64 exec, exec, s[0:1]
	v_mov_b32_e32 v153, v204
	s_waitcnt vmcnt(0)
	s_barrier
	s_cmp_lg_u32 s48, 3
	s_cbranch_scc1 .Lw3_skip
	v_lshlrev_b32_e32 v194, 2, v204
	v_and_b32_e32 v194, 28, v194
	v_lshrrev_b32_e32 v195, 6, v204
	v_and_b32_e32 v195, 3, v195
	v_lshlrev_b32_e32 v195, 5, v195
	v_or3_b32 v194, v194, s72, v195
	v_lshlrev_b32_e32 v194, 2, v194
	v_mov_b32_e32 v195, 0
	v_readlane_b32 s0, v255, 3
	v_readlane_b32 s1, v255, 4
	v_lshl_add_u64 v[196:197], s[80:81], 0, v[194:195]
	s_nop 1
	v_lshl_add_u64 v[198:199], s[0:1], 0, v[194:195]
	global_load_dwordx4 v[162:165], v[196:197], off
	v_add_co_u32_e32 v200, vcc, 0xb000, v196
	s_nop 1
	v_addc_co_u32_e32 v201, vcc, 0, v197, vcc
	global_load_dwordx4 v[166:169], v[200:201], off
	v_add_co_u32_e32 v200, vcc, 0x16000, v196
	s_nop 1
	v_addc_co_u32_e32 v201, vcc, 0, v197, vcc
	global_load_dwordx4 v[170:173], v[200:201], off
	v_add_co_u32_e32 v200, vcc, 0x5000, v196
	s_nop 1
	v_addc_co_u32_e32 v201, vcc, 0, v197, vcc
	global_load_dwordx4 v[174:177], v[200:201], off offset:2048
	v_add_co_u32_e32 v200, vcc, 0x10000, v196
	s_nop 1
	v_addc_co_u32_e32 v201, vcc, 0, v197, vcc
	global_load_dwordx4 v[178:181], v[200:201], off offset:2048
	v_add_co_u32_e32 v200, vcc, 0x1b000, v196
	s_nop 1
	v_addc_co_u32_e32 v201, vcc, 0, v197, vcc
	global_load_dwordx4 v[182:185], v[200:201], off offset:2048
	global_load_dwordx4 v[186:189], v[198:199], off
	v_add_co_u32_e32 v200, vcc, 0x5000, v198
	s_nop 1
	v_addc_co_u32_e32 v201, vcc, 0, v199, vcc
	global_load_dwordx4 v[190:193], v[200:201], off offset:2048
.Lw3_skip:
	s_add_i32 s24, 0, 0x22000
	v_and_b32_e32 v0, 0xffffff00, v153
	v_and_b32_e32 v130, 48, v153
	v_cndmask_b32_e64 v131, 0, 1, s[4:5]
	v_cmp_ne_u32_e64 s[6:7], 1, v131
	s_andn2_b64 vcc, exec, s[4:5]
	v_add3_u32 v144, s24, v0, v130
	s_mov_b32 s77, s88
	s_mov_b64 s[60:61], s[22:23]
	s_mov_b64 s[62:63], s[16:17]
	s_mov_b64 s[16:17], s[14:15]
	s_cbranch_vccnz .LBB0_466
	ds_read_b32 v130, v144
	s_waitcnt lgkmcnt(0)
	v_mul_f32_e32 v126, v126, v130

; DI void gemm_tile(const GD& g, int pm, int pn, bf16_t* shm) {
;     ...
;       if (g.epi == 3) {
;         const int cgp = lane & 7, rs = lane >> 3, r0 = rs * 8;
;         const int fcol = pn * HALF + wc * 32 + cgp * 4;
;         const float* cw = g.gnext;
;         const float4 wg0 = *reinterpret_cast<const float4*>(cw + fcol), wg1 = *reinterpret_cast<const float4*>(cw + NUP + fcol), wg2 = *reinterpret_cast<const float4*>(cw + 2 * NUP + fcol);
;         const float4 wv0 = *reinterpret_cast<const float4*>(cw + DFF + fcol), wv1 = *reinterpret_cast<const float4*>(cw + NUP + DFF + fcol), wv2 = *reinterpret_cast<const float4*>(cw + 2 * NUP + DFF + fcol);
;         const float4 bg = *reinterpret_cast<const float4*>(g.cbias + fcol), bv = *reinterpret_cast<const float4*>(g.cbias + DFF + fcol);
;         float* carry = (float*)shm + 8 * (64 * 68) + 256;
;         float4 g2, g1, v2, v1;
;         const bool first = (ai == 0 && wr == 0 && rs == 0);
;         {
;           const float* pb;
;           int ra, rb;
;           if (rs > 0) { pb = stgw; ra = r0 - 2; rb = r0 - 1; }
;           else if (wr == 1) { pb = (float*)shm + (wid - 4) * (64 * 68); ra = 62; rb = 63; }
;           else { pb = carry + wc * 128 - 0; ra = 0; rb = 1; }
;           if (rs == 0 && wr == 0) {
;             if (ai == 1) {
;               g2 = *reinterpret_cast<const float4*>(carry + wc * 128 + cgp * 4); v2 = *reinterpret_cast<const float4*>(carry + wc * 128 + 32 + cgp * 4);
;               g1 = *reinterpret_cast<const float4*>(carry + wc * 128 + 64 + cgp * 4); v1 = *reinterpret_cast<const float4*>(carry + wc * 128 + 96 + cgp * 4);
;             } else { g2 = g1 = v2 = v1 = make_float4(0.f, 0.f, 0.f, 0.f); }
;           } else {
;             g2 = *reinterpret_cast<const float4*>(pb + ra * 68 + cgp * 4); v2 = *reinterpret_cast<const float4*>(pb + ra * 68 + 32 + cgp * 4);
;             g1 = *reinterpret_cast<const float4*>(pb + rb * 68 + cgp * 4); v1 = *reinterpret_cast<const float4*>(pb + rb * 68 + 32 + cgp * 4);
;           }
.LBB0_530:
	v_and_b32_e32 v2, 63, v153
	s_movk_i32 s0, 0xff
	v_ashrrev_i32_e32 v3, 8, v153
	v_and_b32_e32 v139, 3, v143
	v_and_b32_e32 v142, 56, v153
	v_lshlrev_b32_e32 v4, 2, v153
	v_cmp_lt_u32_e32 vcc, s0, v153
	v_cmp_lt_u32_e64 s[0:1], 7, v2
	v_lshlrev_b32_e32 v155, 5, v139
	v_and_b32_e32 v146, 28, v4
	s_or_b64 s[52:53], vcc, s[0:1]
	s_movk_i32 s0, 0x44
	v_cmp_eq_u32_e64 s[10:11], 1, v3
	v_cmp_eq_u32_e32 vcc, 56, v142
	v_lshlrev_b32_e32 v154, 6, v3
	v_or3_b32 v130, v146, s72, v155
	v_mad_u32_u24 v147, v142, s0, v229
	v_mad_u32_u24 v148, v142, s0, v230
	v_readlane_b32 s0, v253, 36
	s_and_b64 s[50:51], s[10:11], vcc
	v_add_u32_e32 v140, s18, v154
	v_cmp_eq_u32_e64 s[4:5], 0, v151
	v_ashrrev_i32_e32 v131, 31, v130
	v_cmp_gt_u32_e64 s[8:9], 8, v2
	v_lshl_add_u32 v149, v139, 9, s0
	v_add_u32_e32 v150, 0xfffef000, v141
	s_cmp_lt_i32 s48, 3
	s_mul_i32 s56, s27, 0xb000
	ds_write_b32 v145, v5 offset:14064
	s_waitcnt lgkmcnt(0)
	s_barrier
	s_cbranch_scc1 .LBB0_610
	s_cmp_eq_u32 s48, 3
	s_mov_b64 s[2:3], -1
	s_cbranch_scc0 .LBB0_547
	v_lshlrev_b64 v[2:3], 2, v[130:131]
	v_readlane_b32 s0, v255, 3
	v_lshl_add_u64 v[10:11], s[80:81], 0, v[2:3]
	v_readlane_b32 s1, v255, 4
	v_mov_b32_e32 v120, 0
	s_nop 3
	v_lshl_add_u64 v[14:15], s[0:1], 0, v[2:3]
	v_add_co_u32_e32 v2, vcc, 0xb000, v10
	v_mov_b32_e32 v121, v120
	s_nop 0
	v_addc_co_u32_e32 v3, vcc, 0, v11, vcc
	v_add_co_u32_e32 v4, vcc, 0x16000, v10
	v_mov_b32_e32 v108, v120
	s_nop 0
	v_addc_co_u32_e32 v5, vcc, 0, v11, vcc
	v_add_co_u32_e32 v2, vcc, 0x5000, v10
	v_mov_b32_e32 v109, v120
	s_nop 0
	v_addc_co_u32_e32 v3, vcc, 0, v11, vcc
	v_add_co_u32_e32 v6, vcc, 0x10000, v10
	v_mov_b32_e32 v118, v120
	s_nop 0
	v_addc_co_u32_e32 v7, vcc, 0, v11, vcc
	v_add_co_u32_e32 v10, vcc, 0x1b000, v10
	s_nop 0
	s_nop 3
	v_addc_co_u32_e32 v11, vcc, 0, v11, vcc
	s_nop 0
	v_add_co_u32_e32 v14, vcc, 0x5000, v14
	v_mov_b32_e32 v119, v120
	s_nop 0
	v_addc_co_u32_e32 v15, vcc, 0, v15, vcc
	s_waitcnt vmcnt(0)
	v_mov_b64_e32 v[82:83], v[162:163]
	v_mov_b64_e32 v[84:85], v[164:165]
	v_mov_b64_e32 v[86:87], v[166:167]
	v_mov_b64_e32 v[88:89], v[168:169]
	v_mov_b64_e32 v[90:91], v[170:171]
	v_mov_b64_e32 v[92:93], v[172:173]
	v_mov_b64_e32 v[2:3], v[174:175]
	v_mov_b64_e32 v[4:5], v[176:177]
	v_mov_b64_e32 v[6:7], v[178:179]
	v_mov_b64_e32 v[8:9], v[180:181]
	v_mov_b64_e32 v[10:11], v[182:183]
	v_mov_b64_e32 v[12:13], v[184:185]
	v_mov_b64_e32 v[94:95], v[186:187]
	v_mov_b64_e32 v[96:97], v[188:189]
	v_mov_b64_e32 v[14:15], v[190:191]
	v_mov_b64_e32 v[16:17], v[192:193]
	v_mov_b32_e32 v106, v120
	v_mov_b32_e32 v107, v120
	v_mov_b32_e32 v116, v120
	v_mov_b32_e32 v117, v120
	v_mov_b32_e32 v104, v120
	v_mov_b32_e32 v105, v120
	v_mov_b32_e32 v114, v120
	v_mov_b32_e32 v115, v120
	v_mov_b32_e32 v102, v120
	v_mov_b32_e32 v103, v120
	s_and_saveexec_b64 s[0:1], s[52:53]
	s_cbranch_execz .LBB0_534
	v_cndmask_b32_e64 v98, v231, v232, s[10:11]
	v_cndmask_b32_e64 v99, 0, v233, s[10:11]
	v_cndmask_b32_e64 v98, v148, v98, s[8:9]
	v_cndmask_b32_e64 v99, v147, v99, s[8:9]
	v_cndmask_b32_e64 v100, v149, v150, s[10:11]
	v_cndmask_b32_e64 v100, v141, v100, s[8:9]
	v_lshlrev_b32_e32 v99, 2, v99
	v_lshlrev_b32_e32 v101, 2, v146
	v_lshlrev_b32_e32 v98, 2, v98
	v_add3_u32 v99, v100, v99, v101
	v_add3_u32 v98, v100, v98, v101
	ds_read_b128 v[114:117], v99
	ds_read_b128 v[102:105], v99 offset:128
	ds_read_b128 v[118:121], v98
	ds_read_b128 v[106:109], v98 offset:128

; DI void gemm_tile(const GD& g, int pm, int pn, bf16_t* shm) {
;     ...
;         const float4 wg0 = *reinterpret_cast<const float4*>(cw + fcol), wg1 = *reinterpret_cast<const float4*>(cw + NUP + fcol), wg2 = *reinterpret_cast<const float4*>(cw + 2 * NUP + fcol);
;         const float4 wv0 = *reinterpret_cast<const float4*>(cw + DFF + fcol), wv1 = *reinterpret_cast<const float4*>(cw + NUP + DFF + fcol), wv2 = *reinterpret_cast<const float4*>(cw + 2 * NUP + DFF + fcol);
;         const float4 bg = *reinterpret_cast<const float4*>(g.cbias + fcol), bv = *reinterpret_cast<const float4*>(g.cbias + DFF + fcol);
;         float* carry = (float*)shm + 8 * (64 * 68) + 256;
;         float4 g2, g1, v2, v1;
;         const bool first = (ai == 0 && wr == 0 && rs == 0);
;         {
;           const float* pb;
;           int ra, rb;
;           if (rs > 0) { pb = stgw; ra = r0 - 2; rb = r0 - 1; }
;           else if (wr == 1) { pb = (float*)shm + (wid - 4) * (64 * 68); ra = 62; rb = 63; }
;           else { pb = carry + wc * 128 - 0; ra = 0; rb = 1; }
;           if (rs == 0 && wr == 0) {
;             if (ai == 1) {
;               g2 = *reinterpret_cast<const float4*>(carry + wc * 128 + cgp * 4); v2 = *reinterpret_cast<const float4*>(carry + wc * 128 + 32 + cgp * 4);
;               g1 = *reinterpret_cast<const float4*>(carry + wc * 128 + 64 + cgp * 4); v1 = *reinterpret_cast<const float4*>(carry + wc * 128 + 96 + cgp * 4);
;             } else { g2 = g1 = v2 = v1 = make_float4(0.f, 0.f, 0.f, 0.f); }
;           } else {
;             g2 = *reinterpret_cast<const float4*>(pb + ra * 68 + cgp * 4); v2 = *reinterpret_cast<const float4*>(pb + ra * 68 + 32 + cgp * 4);
;             g1 = *reinterpret_cast<const float4*>(pb + rb * 68 + cgp * 4); v1 = *reinterpret_cast<const float4*>(pb + rb * 68 + 32 + cgp * 4);
;           }
;         }
;         float* halo = g.halo + (size_t)pm * 4 * NUP;
; #pragma unroll
;         for (int rr = 0; rr < 8; ++rr) {
;           const int row_l = r0 + rr;
;           const float4 gc = *reinterpret_cast<const float4*>(stgw + row_l * 68 + cgp * 4);
;           const float4 vc = *reinterpret_cast<const float4*>(stgw + row_l * 68 + 32 + cgp * 4);
;           const int grow = brow + ai * HALF + wr * 64 + row_l;
;           if (!(first && rr < 2)) {
.LBB0_1010:
	s_cmp_lt_i32 s48, 3
	ds_write_b32 v145, v21 offset:14064
	s_waitcnt lgkmcnt(0)
	s_barrier
	s_cbranch_scc1 .LBB0_1020
	s_cmp_eq_u32 s48, 3
	s_mov_b64 s[2:3], -1
	s_cbranch_scc0 .LBB0_1019
	v_lshlrev_b64 v[18:19], 2, v[130:131]
	v_readlane_b32 s2, v255, 3
	v_lshl_add_u64 v[26:27], s[80:81], 0, v[18:19]
	v_readlane_b32 s3, v255, 4
	s_nop 0
	s_nop 3
	v_lshl_add_u64 v[30:31], s[2:3], 0, v[18:19]
	v_add_co_u32_e32 v18, vcc, 0xb000, v26
	v_readlane_b32 s2, v253, 36
	s_nop 0
	v_addc_co_u32_e32 v19, vcc, 0, v27, vcc
	v_add_co_u32_e32 v20, vcc, 0x16000, v26
	v_lshl_add_u32 v50, v143, 9, s2
	s_nop 0
	v_addc_co_u32_e32 v21, vcc, 0, v27, vcc
	v_add_co_u32_e32 v18, vcc, 0x5000, v26
	v_add_u32_e32 v0, 0x100, v50
	s_nop 0
	v_addc_co_u32_e32 v19, vcc, 0, v27, vcc
	v_add_co_u32_e32 v22, vcc, 0x10000, v26
	v_add_u32_e32 v51, 0x180, v50
	s_nop 0
	v_addc_co_u32_e32 v23, vcc, 0, v27, vcc
	v_add_co_u32_e32 v26, vcc, 0x1b000, v26
	s_nop 0
	s_nop 3
	v_addc_co_u32_e32 v27, vcc, 0, v27, vcc
	s_nop 0
	v_add_co_u32_e32 v30, vcc, 0x5000, v30
	s_nop 1
	v_addc_co_u32_e32 v31, vcc, 0, v31, vcc
	s_waitcnt vmcnt(0)
	v_mov_b64_e32 v[34:35], v[162:163]
	v_mov_b64_e32 v[36:37], v[164:165]
	v_mov_b64_e32 v[38:39], v[166:167]
	v_mov_b64_e32 v[40:41], v[168:169]
	v_mov_b64_e32 v[42:43], v[170:171]
	v_mov_b64_e32 v[44:45], v[172:173]
	v_mov_b64_e32 v[18:19], v[174:175]
	v_mov_b64_e32 v[20:21], v[176:177]
	v_mov_b64_e32 v[22:23], v[178:179]
	v_mov_b64_e32 v[24:25], v[180:181]
	v_mov_b64_e32 v[26:27], v[182:183]
	v_mov_b64_e32 v[28:29], v[184:185]
	v_mov_b64_e32 v[46:47], v[186:187]
	v_mov_b64_e32 v[48:49], v[188:189]
	v_mov_b64_e32 v[30:31], v[190:191]
	v_mov_b64_e32 v[32:33], v[192:193]
	s_and_saveexec_b64 s[2:3], s[52:53]
	v_cndmask_b32_e64 v0, v231, v232, s[10:11]
	v_cndmask_b32_e64 v51, v149, v150, s[10:11]
	v_cndmask_b32_e64 v0, v148, v0, s[8:9]
	v_cndmask_b32_e64 v50, 0, v233, s[10:11]
	v_cndmask_b32_e64 v51, v141, v51, s[8:9]
	v_cndmask_b32_e64 v50, v147, v50, s[8:9]
	v_lshl_add_u32 v0, v0, 2, v51
	v_lshl_add_u32 v50, v50, 2, v51
	v_add_u32_e32 v51, 0x80, v0
	s_or_b64 exec, exec, s[2:3]
	v_lshlrev_b32_e32 v78, 2, v146
	v_add_u32_e32 v51, v51, v78
	v_add_u32_e32 v52, v0, v78
	v_mul_u32_u24_e32 v53, 0x110, v142
	v_add_u32_e32 v70, v50, v78
	v_add3_u32 v79, v141, v53, v78
	ds_read_b128 v[58:61], v51
	ds_read_b128 v[66:69], v52
	ds_read_b128 v[62:65], v79
	ds_read_b128 v[50:53], v79 offset:128
	ds_read_b128 v[54:57], v70 offset:128
	ds_read_b128 v[70:73], v70
	s_lshl_b64 s[2:3], s[56:57], 2
	v_readlane_b32 s6, v255, 5
	v_readlane_b32 s7, v255, 6
	s_add_u32 s6, s6, s2
	s_waitcnt vmcnt(1) lgkmcnt(0)
	v_pk_fma_f32 v[70:71], v[34:35], v[70:71], v[46:47]
	s_addc_u32 s7, s7, s3
	v_pk_fma_f32 v[70:71], v[38:39], v[66:67], v[70:71]
	s_waitcnt vmcnt(0)
	v_pk_fma_f32 v[54:55], v[18:19], v[54:55], v[30:31]
	v_pk_fma_f32 v[70:71], v[42:43], v[62:63], v[70:71]
	v_pk_fma_f32 v[54:55], v[22:23], v[58:59], v[54:55]
	v_mul_f32_e32 v74, 0xbfb8aa3b, v70
	v_mul_f32_e32 v75, 0xbfb8aa3b, v71
	v_exp_f32_e32 v74, v74
	v_exp_f32_e32 v75, v75
	v_pk_fma_f32 v[54:55], v[26:27], v[50:51], v[54:55]
	v_pk_fma_f32 v[56:57], v[20:21], v[56:57], v[32:33]
	v_add_u32_e32 v0, 0x80, v140
	v_pk_add_f32 v[74:75], v[74:75], 1.0 op_sel_hi:[1,0]
	v_pk_fma_f32 v[56:57], v[24:25], v[60:61], v[56:57]
	v_pk_fma_f32 v[56:57], v[28:29], v[52:53], v[56:57]
	v_or_b32_e32 v88, v0, v142
	s_movk_i32 s8, 0x2c00
	v_rcp_f32_e32 v76, v75
	s_nop 0
	v_mul_f32_e32 v71, v71, v76
	v_mov_b64_e32 v[82:83], s[34:35]
	v_lshlrev_b64 v[84:85], 1, v[130:131]
	v_pk_fma_f32 v[66:67], v[34:35], v[66:67], v[46:47]
	v_rcp_f32_e32 v75, v74
	s_nop 0
	v_mul_f32_e32 v70, v70, v75
	v_pk_mul_f32 v[54:55], v[54:55], v[70:71]
	v_pk_fma_f32 v[70:71], v[36:37], v[72:73], v[48:49]
	v_cvt_pk_bf16_f32 v54, v54, v55
	v_pk_fma_f32 v[70:71], v[40:41], v[68:69], v[70:71]
	v_pk_fma_f32 v[66:67], v[38:39], v[62:63], v[66:67]
	v_pk_fma_f32 v[70:71], v[44:45], v[64:65], v[70:71]
	v_pk_fma_f32 v[58:59], v[18:19], v[58:59], v[30:31]
	v_mul_f32_e32 v72, 0xbfb8aa3b, v70
	v_mul_f32_e32 v73, 0xbfb8aa3b, v71
	v_exp_f32_e32 v72, v72
	v_exp_f32_e32 v73, v73
	v_pk_fma_f32 v[58:59], v[22:23], v[50:51], v[58:59]
	v_pk_fma_f32 v[60:61], v[20:21], v[60:61], v[32:33]
	v_pk_fma_f32 v[62:63], v[34:35], v[62:63], v[46:47]
	v_pk_add_f32 v[72:73], v[72:73], 1.0 op_sel_hi:[1,0]
	v_pk_fma_f32 v[60:61], v[24:25], v[52:53], v[60:61]
	v_pk_fma_f32 v[50:51], v[18:19], v[50:51], v[30:31]
	v_pk_fma_f32 v[52:53], v[20:21], v[52:53], v[32:33]
	v_rcp_f32_e32 v74, v73
	s_nop 0
	v_mul_f32_e32 v71, v71, v74
	s_nop 0
	v_rcp_f32_e32 v73, v72
	s_nop 0
	v_mul_f32_e32 v70, v70, v73
	v_pk_mul_f32 v[56:57], v[56:57], v[70:71]
	v_or_b32_e32 v76, 1, v88
	v_cvt_pk_bf16_f32 v55, v56, v57
	v_mad_i64_i32 v[56:57], s[2:3], v88, s8, v[82:83]
	v_lshl_add_u64 v[56:57], v[56:57], 0, v[84:85]
	global_store_dwordx2 v[56:57], v[54:55], off
	ds_read_b128 v[70:73], v79 offset:272
	ds_read_b128 v[54:57], v79 offset:400
	s_waitcnt lgkmcnt(1)
	v_pk_fma_f32 v[66:67], v[42:43], v[70:71], v[66:67]
	s_nop 0
	v_mul_f32_e32 v74, 0xbfb8aa3b, v66
	v_mul_f32_e32 v75, 0xbfb8aa3b, v67
	v_exp_f32_e32 v74, v74
	v_exp_f32_e32 v75, v75
	s_waitcnt lgkmcnt(0)
; DI unsigned pk2(float a, float b) { f32x2 v; v[0] = a; v[1] = b; return __builtin_bit_cast(unsigned, __builtin_convertvector(v, bf16v2)); }
; DI float siluf_(float x) { return x / (1.f + __expf(-x)); }
; DI void gemm_tile(const GD& g, int pm, int pn, bf16_t* shm) {
;     ...
;         for (int rr = 0; rr < 8; ++rr) {
;           const int row_l = r0 + rr;
;           const float4 gc = *reinterpret_cast<const float4*>(stgw + row_l * 68 + cgp * 4);
;           const float4 vc = *reinterpret_cast<const float4*>(stgw + row_l * 68 + 32 + cgp * 4);
;           const int grow = brow + ai * HALF + wr * 64 + row_l;
;           if (!(first && rr < 2)) {
;             const float a0 = siluf_(bg.x + wg0.x * g2.x + wg1.x * g1.x + wg2.x * gc.x) * (bv.x + wv0.x * v2.x + wv1.x * v1.x + wv2.x * vc.x);
;             const float a1 = siluf_(bg.y + wg0.y * g2.y + wg1.y * g1.y + wg2.y * gc.y) * (bv.y + wv0.y * v2.y + wv1.y * v1.y + wv2.y * vc.y);
;             const float a2 = siluf_(bg.z + wg0.z * g2.z + wg1.z * g1.z + wg2.z * gc.z) * (bv.z + wv0.z * v2.z + wv1.z * v1.z + wv2.z * vc.z);
;             const float a3 = siluf_(bg.w + wg0.w * g2.w + wg1.w * g1.w + wg2.w * gc.w) * (bv.w + wv0.w * v2.w + wv1.w * v1.w + wv2.w * vc.w);
;             u32x2 o2; o2[0] = pk2(a0, a1); o2[1] = pk2(a2, a3);
;             *reinterpret_cast<u32x2*>((bf16_t*)g.C + (long)grow * DFF + fcol) = o2;
;           }
;           if (first && rr < 2) {
;             *reinterpret_cast<float4*>(halo + (size_t)rr * NUP + fcol) = gc; *reinterpret_cast<float4*>(halo + (size_t)rr * NUP + DFF + fcol) = vc;
;           }
;           if (ai == 1 && wr == 1 && rs == 7 && rr >= 6) {
;             *reinterpret_cast<float4*>(halo + (size_t)(rr - 4) * NUP + fcol) = gc; *reinterpret_cast<float4*>(halo + (size_t)(rr - 4) * NUP + DFF + fcol) = vc;
;           }
;           if (ai == 0 && wr == 1 && rs == 7 && rr >= 6) {
;             *reinterpret_cast<float4*>(carry + wc * 128 + (rr - 6) * 64 + cgp * 4) = gc; *reinterpret_cast<float4*>(carry + wc * 128 + (rr - 6) * 64 + 32 + cgp * 4) = vc;
;           }
;           g2 = g1; g1 = gc; v2 = v1; v1 = vc;
	v_pk_fma_f32 v[58:59], v[26:27], v[54:55], v[58:59]
	v_pk_fma_f32 v[60:61], v[28:29], v[56:57], v[60:61]
	v_pk_fma_f32 v[62:63], v[38:39], v[70:71], v[62:63]
	v_pk_add_f32 v[74:75], v[74:75], 1.0 op_sel_hi:[1,0]
	v_pk_fma_f32 v[50:51], v[22:23], v[54:55], v[50:51]
	v_pk_fma_f32 v[52:53], v[24:25], v[56:57], v[52:53]
	v_rcp_f32_e32 v77, v75
	s_nop 0
	v_mul_f32_e32 v67, v67, v77
	s_nop 0
	v_rcp_f32_e32 v75, v74
	s_nop 0
	v_mul_f32_e32 v66, v66, v75
	v_pk_mul_f32 v[58:59], v[66:67], v[58:59]
	v_pk_fma_f32 v[66:67], v[36:37], v[68:69], v[48:49]
	v_cvt_pk_bf16_f32 v58, v58, v59
	v_pk_fma_f32 v[66:67], v[40:41], v[64:65], v[66:67]
	s_nop 0
	v_pk_fma_f32 v[66:67], v[44:45], v[72:73], v[66:67]
	s_nop 0
	v_mul_f32_e32 v68, 0xbfb8aa3b, v66
	v_mul_f32_e32 v69, 0xbfb8aa3b, v67
	v_exp_f32_e32 v68, v68
	v_exp_f32_e32 v69, v69
	s_nop 0
	v_pk_add_f32 v[68:69], v[68:69], 1.0 op_sel_hi:[1,0]
	s_nop 0
	s_nop 0
	v_rcp_f32_e32 v74, v69
	s_nop 0
	v_mul_f32_e32 v67, v67, v74
	s_nop 0
	v_rcp_f32_e32 v69, v68
	s_nop 0
	v_mul_f32_e32 v66, v66, v69
	v_pk_mul_f32 v[60:61], v[66:67], v[60:61]
	v_or_b32_e32 v68, 2, v88
	v_cvt_pk_bf16_f32 v59, v60, v61
	v_mad_i64_i32 v[60:61], s[2:3], v76, s8, v[82:83]
	v_lshl_add_u64 v[60:61], v[60:61], 0, v[84:85]
	global_store_dwordx2 v[60:61], v[58:59], off
	ds_read_b128 v[74:77], v79 offset:544
	ds_read_b128 v[58:61], v79 offset:672
	s_waitcnt lgkmcnt(1)
	v_pk_fma_f32 v[62:63], v[42:43], v[74:75], v[62:63]
	s_nop 0
	v_mul_f32_e32 v66, 0xbfb8aa3b, v62
	v_mul_f32_e32 v67, 0xbfb8aa3b, v63
	v_exp_f32_e32 v66, v66
	v_exp_f32_e32 v67, v67
	s_waitcnt lgkmcnt(0)
	v_pk_fma_f32 v[50:51], v[26:27], v[58:59], v[50:51]
	v_pk_fma_f32 v[52:53], v[28:29], v[60:61], v[52:53]
	v_pk_add_f32 v[66:67], v[66:67], 1.0 op_sel_hi:[1,0]
	s_nop 0
	s_nop 0
	v_rcp_f32_e32 v69, v67
	s_nop 0
	v_mul_f32_e32 v63, v63, v69
	s_nop 0
	v_rcp_f32_e32 v67, v66
	s_nop 0
	v_mul_f32_e32 v62, v62, v67
	v_pk_mul_f32 v[50:51], v[62:63], v[50:51]
	v_pk_fma_f32 v[62:63], v[36:37], v[64:65], v[48:49]
	v_cvt_pk_bf16_f32 v50, v50, v51
	v_pk_fma_f32 v[62:63], v[40:41], v[72:73], v[62:63]
	s_nop 0
	v_pk_fma_f32 v[62:63], v[44:45], v[76:77], v[62:63]
	s_nop 0
	v_mul_f32_e32 v64, 0xbfb8aa3b, v62
	v_mul_f32_e32 v65, 0xbfb8aa3b, v63
	v_exp_f32_e32 v64, v64
	v_exp_f32_e32 v65, v65
	s_nop 0
	v_pk_add_f32 v[64:65], v[64:65], 1.0 op_sel_hi:[1,0]
	s_nop 0
	s_nop 0
	v_rcp_f32_e32 v66, v65
	s_nop 0
	v_mul_f32_e32 v63, v63, v66
	s_nop 0
	v_rcp_f32_e32 v65, v64
	s_nop 0
	v_mul_f32_e32 v62, v62, v65
	v_pk_mul_f32 v[52:53], v[62:63], v[52:53]
	v_or_b32_e32 v80, 3, v88
	v_cvt_pk_bf16_f32 v51, v52, v53
	v_mad_i64_i32 v[52:53], s[2:3], v68, s8, v[82:83]
	v_lshl_add_u64 v[52:53], v[52:53], 0, v[84:85]
	global_store_dwordx2 v[52:53], v[50:51], off
	ds_read_b128 v[62:65], v79 offset:816
	ds_read_b128 v[66:69], v79 offset:944
	v_pk_fma_f32 v[50:51], v[34:35], v[70:71], v[46:47]
	s_nop 0
	v_pk_fma_f32 v[50:51], v[38:39], v[74:75], v[50:51]
	s_waitcnt lgkmcnt(1)
	v_pk_fma_f32 v[50:51], v[42:43], v[62:63], v[50:51]
	s_nop 0
	v_mul_f32_e32 v52, 0xbfb8aa3b, v50
	v_mul_f32_e32 v53, 0xbfb8aa3b, v51
	v_exp_f32_e32 v52, v52
	v_exp_f32_e32 v53, v53
	s_nop 0
	v_pk_add_f32 v[52:53], v[52:53], 1.0 op_sel_hi:[1,0]
	s_nop 0
	s_nop 0
	v_rcp_f32_e32 v70, v53
	s_nop 0
	v_mul_f32_e32 v51, v51, v70
	s_nop 0
	v_rcp_f32_e32 v53, v52
	s_nop 0
	v_mul_f32_e32 v50, v50, v53
	v_pk_fma_f32 v[52:53], v[18:19], v[54:55], v[30:31]
	s_nop 0
	v_pk_fma_f32 v[52:53], v[22:23], v[58:59], v[52:53]
	s_waitcnt lgkmcnt(0)
	v_pk_fma_f32 v[52:53], v[26:27], v[66:67], v[52:53]
	s_nop 0
	v_pk_mul_f32 v[50:51], v[50:51], v[52:53]
	v_pk_fma_f32 v[52:53], v[36:37], v[72:73], v[48:49]
	v_cvt_pk_bf16_f32 v50, v50, v51
	v_pk_fma_f32 v[52:53], v[40:41], v[76:77], v[52:53]
	s_nop 0
	v_pk_fma_f32 v[52:53], v[44:45], v[64:65], v[52:53]
	s_nop 0
	v_mul_f32_e32 v54, 0xbfb8aa3b, v52
	v_mul_f32_e32 v55, 0xbfb8aa3b, v53
	v_exp_f32_e32 v54, v54
	v_exp_f32_e32 v55, v55
	s_nop 0
	v_pk_add_f32 v[54:55], v[54:55], 1.0 op_sel_hi:[1,0]
	s_nop 0
	s_nop 0
	v_rcp_f32_e32 v70, v55
	s_nop 0
	v_mul_f32_e32 v53, v53, v70
	s_nop 0
	v_rcp_f32_e32 v55, v54
	s_nop 0
	v_mul_f32_e32 v52, v52, v55
	v_pk_fma_f32 v[54:55], v[20:21], v[56:57], v[32:33]
	s_nop 0
	v_pk_fma_f32 v[54:55], v[24:25], v[60:61], v[54:55]
	s_nop 0
	v_pk_fma_f32 v[54:55], v[28:29], v[68:69], v[54:55]
	s_nop 0
	v_pk_mul_f32 v[52:53], v[52:53], v[54:55]
	v_pk_fma_f32 v[54:55], v[34:35], v[74:75], v[46:47]
	v_cvt_pk_bf16_f32 v51, v52, v53
	v_mad_i64_i32 v[52:53], s[2:3], v80, s8, v[82:83]
	v_lshl_add_u64 v[52:53], v[52:53], 0, v[84:85]
	global_store_dwordx2 v[52:53], v[50:51], off
	ds_read_b128 v[70:73], v79 offset:1088
	ds_read_b128 v[50:53], v79 offset:1216
	v_pk_fma_f32 v[54:55], v[38:39], v[62:63], v[54:55]
	v_or_b32_e32 v80, 4, v88
	v_pk_fma_f32 v[62:63], v[34:35], v[62:63], v[46:47]
	s_waitcnt lgkmcnt(1)
	v_pk_fma_f32 v[54:55], v[42:43], v[70:71], v[54:55]
	v_pk_fma_f32 v[62:63], v[38:39], v[70:71], v[62:63]
	v_mul_f32_e32 v56, 0xbfb8aa3b, v54
	v_mul_f32_e32 v57, 0xbfb8aa3b, v55
	v_exp_f32_e32 v56, v56
	v_exp_f32_e32 v57, v57
	s_nop 0
	v_pk_add_f32 v[56:57], v[56:57], 1.0 op_sel_hi:[1,0]
	s_nop 0
	s_nop 0
	v_rcp_f32_e32 v74, v57
	s_nop 0
	v_mul_f32_e32 v55, v55, v74
	s_nop 0
	v_rcp_f32_e32 v57, v56
	s_nop 0
	v_mul_f32_e32 v54, v54, v57
	v_pk_fma_f32 v[56:57], v[18:19], v[58:59], v[30:31]
	s_nop 0
	v_pk_fma_f32 v[56:57], v[22:23], v[66:67], v[56:57]
	v_pk_fma_f32 v[66:67], v[18:19], v[66:67], v[30:31]
	s_waitcnt lgkmcnt(0)
; DI unsigned pk2(float a, float b) { f32x2 v; v[0] = a; v[1] = b; return __builtin_bit_cast(unsigned, __builtin_convertvector(v, bf16v2)); }
; DI float siluf_(float x) { return x / (1.f + __expf(-x)); }
; DI void gemm_tile(const GD& g, int pm, int pn, bf16_t* shm) {
;     ...
;         for (int rr = 0; rr < 8; ++rr) {
;           const int row_l = r0 + rr;
;           const float4 gc = *reinterpret_cast<const float4*>(stgw + row_l * 68 + cgp * 4);
;           const float4 vc = *reinterpret_cast<const float4*>(stgw + row_l * 68 + 32 + cgp * 4);
;           const int grow = brow + ai * HALF + wr * 64 + row_l;
;           if (!(first && rr < 2)) {
;             const float a0 = siluf_(bg.x + wg0.x * g2.x + wg1.x * g1.x + wg2.x * gc.x) * (bv.x + wv0.x * v2.x + wv1.x * v1.x + wv2.x * vc.x);
;             const float a1 = siluf_(bg.y + wg0.y * g2.y + wg1.y * g1.y + wg2.y * gc.y) * (bv.y + wv0.y * v2.y + wv1.y * v1.y + wv2.y * vc.y);
;             const float a2 = siluf_(bg.z + wg0.z * g2.z + wg1.z * g1.z + wg2.z * gc.z) * (bv.z + wv0.z * v2.z + wv1.z * v1.z + wv2.z * vc.z);
;             const float a3 = siluf_(bg.w + wg0.w * g2.w + wg1.w * g1.w + wg2.w * gc.w) * (bv.w + wv0.w * v2.w + wv1.w * v1.w + wv2.w * vc.w);
;             u32x2 o2; o2[0] = pk2(a0, a1); o2[1] = pk2(a2, a3);
;             *reinterpret_cast<u32x2*>((bf16_t*)g.C + (long)grow * DFF + fcol) = o2;
;           }
;           if (first && rr < 2) {
;             *reinterpret_cast<float4*>(halo + (size_t)rr * NUP + fcol) = gc; *reinterpret_cast<float4*>(halo + (size_t)rr * NUP + DFF + fcol) = vc;
;           }
;           if (ai == 1 && wr == 1 && rs == 7 && rr >= 6) {
;             *reinterpret_cast<float4*>(halo + (size_t)(rr - 4) * NUP + fcol) = gc; *reinterpret_cast<float4*>(halo + (size_t)(rr - 4) * NUP + DFF + fcol) = vc;
;           }
;           if (ai == 0 && wr == 1 && rs == 7 && rr >= 6) {
;             *reinterpret_cast<float4*>(carry + wc * 128 + (rr - 6) * 64 + cgp * 4) = gc; *reinterpret_cast<float4*>(carry + wc * 128 + (rr - 6) * 64 + 32 + cgp * 4) = vc;
	v_pk_fma_f32 v[56:57], v[26:27], v[50:51], v[56:57]
	v_pk_fma_f32 v[66:67], v[22:23], v[50:51], v[66:67]
	v_pk_mul_f32 v[54:55], v[54:55], v[56:57]
	v_pk_fma_f32 v[56:57], v[36:37], v[76:77], v[48:49]
	v_cvt_pk_bf16_f32 v54, v54, v55
	v_pk_fma_f32 v[56:57], v[40:41], v[64:65], v[56:57]
	v_pk_fma_f32 v[64:65], v[36:37], v[64:65], v[48:49]
	v_pk_fma_f32 v[56:57], v[44:45], v[72:73], v[56:57]
	v_pk_fma_f32 v[64:65], v[40:41], v[72:73], v[64:65]
	v_mul_f32_e32 v58, 0xbfb8aa3b, v56
	v_mul_f32_e32 v59, 0xbfb8aa3b, v57
	v_exp_f32_e32 v58, v58
	v_exp_f32_e32 v59, v59
	v_pk_fma_f32 v[50:51], v[18:19], v[50:51], v[30:31]
	v_pk_add_f32 v[58:59], v[58:59], 1.0 op_sel_hi:[1,0]
	s_nop 0
	s_nop 0
	v_rcp_f32_e32 v74, v59
	s_nop 0
	v_mul_f32_e32 v57, v57, v74
	s_nop 0
	v_rcp_f32_e32 v59, v58
	s_nop 0
	v_mul_f32_e32 v56, v56, v59
	v_pk_fma_f32 v[58:59], v[20:21], v[60:61], v[32:33]
	s_nop 0
	v_pk_fma_f32 v[58:59], v[24:25], v[68:69], v[58:59]
	s_nop 0
	v_pk_fma_f32 v[58:59], v[28:29], v[52:53], v[58:59]
	s_nop 0
	v_pk_mul_f32 v[56:57], v[56:57], v[58:59]
	s_nop 0
	v_cvt_pk_bf16_f32 v55, v56, v57
	v_mad_i64_i32 v[56:57], s[2:3], v80, s8, v[82:83]
	v_lshl_add_u64 v[56:57], v[56:57], 0, v[84:85]
	global_store_dwordx2 v[56:57], v[54:55], off
	v_or_b32_e32 v54, 5, v88
	v_mad_i64_i32 v[54:55], s[2:3], v54, s8, v[82:83]
	s_movk_i32 s2, 0x110
	v_lshl_add_u64 v[86:87], v[54:55], 0, v[84:85]
	v_mad_u32_u24 v54, v142, s2, v234
	v_add3_u32 v89, v141, v54, v78
	ds_read_b128 v[58:61], v79 offset:1360
	ds_read_b128 v[54:57], v79 offset:1488
	s_waitcnt lgkmcnt(1)
	v_pk_fma_f32 v[62:63], v[42:43], v[58:59], v[62:63]
	s_nop 0
	v_mul_f32_e32 v74, 0xbfb8aa3b, v62
	v_mul_f32_e32 v75, 0xbfb8aa3b, v63
	v_exp_f32_e32 v74, v74
	v_exp_f32_e32 v75, v75
	s_waitcnt lgkmcnt(0)
	v_pk_fma_f32 v[66:67], v[26:27], v[54:55], v[66:67]
	v_pk_fma_f32 v[64:65], v[44:45], v[60:61], v[64:65]
	v_pk_fma_f32 v[50:51], v[22:23], v[54:55], v[50:51]
	v_pk_add_f32 v[74:75], v[74:75], 1.0 op_sel_hi:[1,0]
	s_nop 0
	s_nop 0
	v_rcp_f32_e32 v76, v75
	s_nop 0
	v_mul_f32_e32 v63, v63, v76
	s_nop 0
	v_rcp_f32_e32 v75, v74
	s_nop 0
	v_mul_f32_e32 v62, v62, v75
	v_pk_mul_f32 v[62:63], v[62:63], v[66:67]
	v_pk_fma_f32 v[66:67], v[20:21], v[68:69], v[32:33]
	v_cvt_pk_bf16_f32 v62, v62, v63
	v_mul_f32_e32 v63, 0xbfb8aa3b, v64
	v_exp_f32_e32 v68, v63
	v_mul_f32_e32 v63, 0xbfb8aa3b, v65
	v_exp_f32_e32 v69, v63
	v_pk_fma_f32 v[66:67], v[24:25], v[52:53], v[66:67]
	ds_read_b128 v[78:81], v89
	ds_read_b128 v[74:77], v89 offset:128
	v_pk_fma_f32 v[66:67], v[28:29], v[56:57], v[66:67]
	v_pk_add_f32 v[68:69], v[68:69], 1.0 op_sel_hi:[1,0]
	v_pk_fma_f32 v[52:53], v[20:21], v[52:53], v[32:33]
	s_waitcnt lgkmcnt(0)
	v_pk_fma_f32 v[50:51], v[26:27], v[74:75], v[50:51]
	v_pk_fma_f32 v[52:53], v[24:25], v[56:57], v[52:53]
	v_rcp_f32_e32 v63, v69
	s_nop 0
	v_mul_f32_e32 v65, v65, v63
	v_pk_fma_f32 v[52:53], v[28:29], v[76:77], v[52:53]
	v_rcp_f32_e32 v63, v68
	s_nop 0
	v_mul_f32_e32 v64, v64, v63
	v_pk_mul_f32 v[64:65], v[64:65], v[66:67]
	v_or_b32_e32 v66, 6, v88
	v_cvt_pk_bf16_f32 v63, v64, v65
	global_store_dwordx2 v[86:87], v[62:63], off
	v_pk_fma_f32 v[62:63], v[34:35], v[70:71], v[46:47]
	s_nop 0
	v_pk_fma_f32 v[62:63], v[38:39], v[58:59], v[62:63]
	s_nop 0
	v_pk_fma_f32 v[62:63], v[42:43], v[78:79], v[62:63]
	s_nop 0
	v_mul_f32_e32 v64, 0xbfb8aa3b, v62
	v_mul_f32_e32 v65, 0xbfb8aa3b, v63
	v_exp_f32_e32 v64, v64
	v_exp_f32_e32 v65, v65
	s_nop 0
	v_pk_add_f32 v[64:65], v[64:65], 1.0 op_sel_hi:[1,0]
	s_nop 0
	s_nop 0
	v_rcp_f32_e32 v67, v65
	s_nop 0
	v_mul_f32_e32 v63, v63, v67
	s_nop 0
	v_rcp_f32_e32 v65, v64
	s_nop 0
	v_mul_f32_e32 v62, v62, v65
	v_pk_mul_f32 v[50:51], v[62:63], v[50:51]
	v_pk_fma_f32 v[62:63], v[36:37], v[72:73], v[48:49]
	v_cvt_pk_bf16_f32 v50, v50, v51
	v_pk_fma_f32 v[62:63], v[40:41], v[60:61], v[62:63]
	s_nop 0
	v_pk_fma_f32 v[62:63], v[44:45], v[80:81], v[62:63]
	s_nop 0
	v_mul_f32_e32 v64, 0xbfb8aa3b, v62
	v_mul_f32_e32 v65, 0xbfb8aa3b, v63
	v_exp_f32_e32 v64, v64
	v_exp_f32_e32 v65, v65
	s_nop 0
	v_pk_add_f32 v[64:65], v[64:65], 1.0 op_sel_hi:[1,0]
	s_nop 0
	s_nop 0
	v_rcp_f32_e32 v67, v65
	s_nop 0
	v_mul_f32_e32 v63, v63, v67
	s_nop 0
	v_rcp_f32_e32 v65, v64
	s_nop 0
	v_mul_f32_e32 v62, v62, v65
	v_pk_mul_f32 v[52:53], v[62:63], v[52:53]
	s_nop 0
	v_cvt_pk_bf16_f32 v51, v52, v53
	v_mad_i64_i32 v[52:53], s[2:3], v66, s8, v[82:83]
	v_lshl_add_u64 v[52:53], v[52:53], 0, v[84:85]
	v_lshl_add_u64 v[66:67], v[130:131], 2, s[6:7]
	global_store_dwordx2 v[52:53], v[50:51], off
	s_and_saveexec_b64 s[2:3], s[50:51]
	s_cbranch_execz .LBB0_1016
	v_add_co_u32_e32 v50, vcc, 0x16000, v66
	s_nop 1
	v_addc_co_u32_e32 v51, vcc, 0, v67, vcc
	global_store_dwordx4 v[50:51], v[78:81], off
	v_add_co_u32_e32 v50, vcc, 0x1b000, v66
	s_nop 1
	v_addc_co_u32_e32 v51, vcc, 0, v67, vcc
	global_store_dwordx4 v[50:51], v[74:77], off offset:2048
